# stick epilogue gain loads hoisted, DPP row reductions in dilated K-norm, NSA selected/window loops accumulate O in place (no 32 v_mov_b64 per tile)
# speedup vs baseline: 1.0447x; 1.0114x over previous
; #define LAS __attribute__((address_space(3)))
; template <int K> __device__ __forceinline__ float swz_f(float v) { return __uint_as_float(swz_u<K>(__float_as_uint(v))); }
; #define UNPACK8(v, k) const float k##0 = blo(v.x), k##1 = bhi(v.x), k##2 = blo(v.y), k##3 = bhi(v.y), k##4 = blo(v.z), k##5 = bhi(v.z), k##6 = blo(v.w), k##7 = bhi(v.w)
; __device__ __forceinline__ unsigned cvtpk(float lo, float hi) { f32x2_t v = {lo, hi}; bf16x2_t b = __builtin_convertvector(v, bf16x2_t); return __builtin_bit_cast(unsigned, b); }
; template <bool NORM> __device__ __forceinline__ void kv_store(u32x4 kc, u32x4 vc, const float (&g)[8], LAS unsigned char* ksb, LAS unsigned char* vtb, int tid) {
;     const int kl = tid >> 3, ch = tid & 7;
;     if (NORM) { UNPACK8(kc, k); float ss = (k0 * k0 + k1 * k1) + (k2 * k2 + k3 * k3) + (k4 * k4 + k5 * k5) + (k6 * k6 + k7 * k7);
;         ss += swz_f<1>(ss); ss += swz_f<2>(ss); ss += swz_f<4>(ss);
;         const float rs = rsqrtf(ss * (1.f / 64.f) + EPS);
;         kc.x = cvtpk(k0 * rs * g[0], k1 * rs * g[1]); kc.y = cvtpk(k2 * rs * g[2], k3 * rs * g[3]); kc.z = cvtpk(k4 * rs * g[4], k5 * rs * g[5]); kc.w = cvtpk(k6 * rs * g[6], k7 * rs * g[7]); }
;     *(LAS u32x4*)(ksb + kl * KSB + ch * 16) = kc;
;     LAS unsigned short* vp = (LAS unsigned short*)(vtb + (8 * ch) * VTB + kl * 2);
;     vp[0 * (VTB / 2)] = (unsigned short)(vc.x & 0xffffu); vp[1 * (VTB / 2)] = (unsigned short)(vc.x >> 16);
;     vp[2 * (VTB / 2)] = (unsigned short)(vc.y & 0xffffu); vp[3 * (VTB / 2)] = (unsigned short)(vc.y >> 16);
;     vp[4 * (VTB / 2)] = (unsigned short)(vc.z & 0xffffu); vp[5 * (VTB / 2)] = (unsigned short)(vc.z >> 16);
;     vp[6 * (VTB / 2)] = (unsigned short)(vc.w & 0xffffu); vp[7 * (VTB / 2)] = (unsigned short)(vc.w >> 16);
; }
.LBB0_863:
	s_waitcnt vmcnt(1)
	v_and_b32_e32 v53, 0xffff0000, v5
	v_and_b32_e32 v51, 0xffff0000, v4
	v_lshlrev_b32_e32 v52, 16, v5
	v_lshlrev_b32_e32 v50, 16, v4
	v_mov_b32_e32 v54, v53
	v_mov_b32_e32 v55, v51
	v_mov_b32_e32 v48, v52
	v_mov_b32_e32 v49, v50
	v_pk_mul_f32 v[54:55], v[54:55], v[54:55]
	v_and_b32_e32 v57, 0xffff0000, v2
	v_pk_fma_f32 v[48:49], v[48:49], v[48:49], v[54:55]
	v_and_b32_e32 v55, 0xffff0000, v3
	v_lshlrev_b32_e32 v54, 16, v3
	v_lshlrev_b32_e32 v56, 16, v2
	v_mov_b32_e32 v60, v57
	v_mov_b32_e32 v61, v55
	v_mov_b32_e32 v58, v56
	v_mov_b32_e32 v59, v54
	v_pk_mul_f32 v[60:61], v[60:61], v[60:61]
	s_mul_i32 s0, s6, 0x2400
	v_pk_fma_f32 v[58:59], v[58:59], v[58:59], v[60:61]
	s_add_i32 s16, s0, 0
	v_add_f32_e32 v58, v58, v59
	v_add_f32_e32 v49, v49, v58
	v_add_f32_e32 v48, v48, v49
	s_lshl_b32 s0, s6, 9
	s_sub_i32 s9, s16, s0
	s_cmp_ge_u32 s13, s24
	s_cselect_b64 s[4:5], -1, 0
	s_nop 1
	v_add_f32_dpp v48, v48, v48 quad_perm:[1,0,3,2] row_mask:0xf bank_mask:0xf
	s_nop 1
	v_add_f32_dpp v48, v48, v48 quad_perm:[2,3,0,1] row_mask:0xf bank_mask:0xf
	s_nop 1
	v_add_f32_dpp v48, v48, v48 row_half_mirror row_mask:0xf bank_mask:0xf
	v_fmamk_f32 v48, v48, 0x3c800000, v139
	v_mul_f32_e32 v49, 0x4b800000, v48
	v_cmp_gt_f32_e32 vcc, s71, v48
	s_nop 1
	v_cndmask_b32_e32 v48, v48, v49, vcc
	v_rsq_f32_e32 v48, v48
	s_nop 0
	v_mul_f32_e32 v49, 0x45800000, v48
	v_cndmask_b32_e32 v58, v48, v49, vcc
	v_pk_mul_f32 v[48:49], v[58:59], v[56:57] op_sel_hi:[0,1]
	v_pk_mul_f32 v[54:55], v[58:59], v[54:55] op_sel_hi:[0,1]
	v_pk_mul_f32 v[50:51], v[58:59], v[50:51] op_sel_hi:[0,1]
	v_pk_mul_f32 v[52:53], v[58:59], v[52:53] op_sel_hi:[0,1]
	v_pk_mul_f32 v[48:49], v[14:15], v[48:49]
	v_pk_mul_f32 v[54:55], v[96:97], v[54:55]
	v_pk_mul_f32 v[50:51], v[98:99], v[50:51]
	v_pk_mul_f32 v[52:53], v[100:101], v[52:53]
	v_cvt_pk_bf16_f32 v48, v48, v49
	v_cvt_pk_bf16_f32 v49, v54, v55
	v_cvt_pk_bf16_f32 v50, v50, v51
	v_cvt_pk_bf16_f32 v51, v52, v53
	v_add3_u32 v52, s16, v95, v108
	ds_write_b128 v52, v[48:51]
	v_add3_u32 v48, s9, v109, v110
	s_and_b64 vcc, exec, s[4:5]
	s_waitcnt vmcnt(0)
	ds_write_b16 v48, v6 offset:18432
	ds_write_b16_d16_hi v48, v6 offset:18568
	ds_write_b16 v48, v7 offset:18704
	ds_write_b16_d16_hi v48, v7 offset:18840
	ds_write_b16 v48, v8 offset:18976
	ds_write_b16_d16_hi v48, v8 offset:19112
	ds_write_b16 v48, v9 offset:19248
	ds_write_b16_d16_hi v48, v9 offset:19384
	s_waitcnt lgkmcnt(0)
	s_barrier
	s_cbranch_vccnz .LBB0_867
	v_add_u32_e32 v48, s43, v114
	v_cmp_lt_i32_e32 vcc, -1, v48
	v_cmp_gt_i32_e64 s[0:1], s30, v48
	s_and_b64 s[26:27], vcc, s[0:1]
	v_mov_b32_e32 v9, 0
	v_mov_b32_e32 v5, 0
	v_mov_b32_e32 v4, 0
	v_mov_b32_e32 v3, 0
	v_mov_b32_e32 v2, 0
	v_mov_b32_e32 v8, 0
	v_mov_b32_e32 v7, 0
	v_mov_b32_e32 v6, 0
	s_and_saveexec_b64 s[0:1], s[26:27]
	s_cbranch_execz .LBB0_866
	v_mad_u64_u32 v[2:3], s[26:27], s44, v48, 0
	v_lshlrev_b64 v[2:3], 1, v[2:3]
	v_lshl_add_u64 v[4:5], v[102:103], 0, v[2:3]
	v_lshl_add_u64 v[6:7], v[104:105], 0, v[2:3]
	global_load_dwordx4 v[2:5], v[4:5], off
	s_nop 0
	global_load_dwordx4 v[6:9], v[6:7], off

; __device__ __forceinline__ float sum32(float v) { auto rr = __builtin_amdgcn_permlane32_swap(__float_as_uint(v), __float_as_uint(v), false, false); return __uint_as_float(rr[0]) + __uint_as_float(rr[1]); }
; __device__ __forceinline__ unsigned cvtpk(float lo, float hi) { f32x2_t v = {lo, hi}; bf16x2_t b = __builtin_convertvector(v, bf16x2_t); return __builtin_bit_cast(unsigned, b); }
; __device__ __forceinline__ void stick_item(const StickArgs& A, int item, LAS unsigned char* lds, int tid) {
;     ...
;     float ss = 0.f;
; #pragma unroll
;     for (int i = 0; i < 16; ++i) ss += o0[i] * o0[i] + o1[i] * o1[i];
;     ss = sum32(ss);
;     const float rs = rsqrtf(ss * (1.f / 64.f) + EPS); const float* go = A.g_out + 512 + head * 64; bf16_t* dst = A.groups + token * DM + 512 + head * 64;
; #pragma unroll
;     for (int g = 0; g < 4; ++g) { const int d0 = 8 * g + 4 * hh;
;         u32x2 wa; wa.x = cvtpk(o0[4 * g] * rs * go[d0], o0[4 * g + 1] * rs * go[d0 + 1]); wa.y = cvtpk(o0[4 * g + 2] * rs * go[d0 + 2], o0[4 * g + 3] * rs * go[d0 + 3]); *(u32x2*)(dst + d0) = wa;
;         u32x2 wb; wb.x = cvtpk(o1[4 * g] * rs * go[32 + d0], o1[4 * g + 1] * rs * go[32 + d0 + 1]); wb.y = cvtpk(o1[4 * g + 2] * rs * go[32 + d0 + 2], o1[4 * g + 3] * rs * go[32 + d0 + 3]); *(u32x2*)(dst + 32 + d0) = wb; }
.LBB0_898:
	v_mul_f32_e32 v0, v18, v18
	v_mul_f32_e32 v34, v19, v19
	v_fmac_f32_e32 v0, v2, v2
	v_fmac_f32_e32 v34, v3, v3
	v_add_f32_e32 v0, v0, v34
	v_mul_f32_e32 v34, v20, v20
	v_fmac_f32_e32 v34, v4, v4
	v_add_f32_e32 v0, v34, v0
	v_mul_f32_e32 v34, v21, v21
	v_fmac_f32_e32 v34, v5, v5
	v_add_f32_e32 v0, v34, v0
	v_mul_f32_e32 v34, v22, v22
	v_fmac_f32_e32 v34, v6, v6
	v_add_f32_e32 v0, v34, v0
	v_mul_f32_e32 v34, v23, v23
	v_fmac_f32_e32 v34, v7, v7
	v_add_f32_e32 v0, v34, v0
	v_mul_f32_e32 v34, v24, v24
	v_fmac_f32_e32 v34, v8, v8
	v_add_f32_e32 v0, v34, v0
	v_mul_f32_e32 v34, v25, v25
	v_fmac_f32_e32 v34, v9, v9
	v_add_f32_e32 v0, v34, v0
	v_mul_f32_e32 v34, v26, v26
	v_fmac_f32_e32 v34, v10, v10
	v_add_f32_e32 v0, v34, v0
	v_mul_f32_e32 v34, v27, v27
	v_fmac_f32_e32 v34, v11, v11
	v_add_f32_e32 v0, v34, v0
	v_pk_mul_f32 v[34:35], v[28:29], v[28:29]
	v_pk_mul_f32 v[38:39], v[30:31], v[30:31]
	v_pk_fma_f32 v[34:35], v[12:13], v[12:13], v[34:35]
	v_pk_fma_f32 v[38:39], v[14:15], v[14:15], v[38:39]
	v_add_f32_e32 v0, v34, v0
	v_add_f32_e32 v0, v35, v0
	v_pk_mul_f32 v[40:41], v[32:33], v[32:33]
	v_add_f32_e32 v0, v38, v0
	s_lshl_b32 s0, s15, 2
	v_readlane_b32 s4, v255, 17
	v_pk_fma_f32 v[40:41], v[16:17], v[16:17], v[40:41]
	v_add_f32_e32 v0, v39, v0
	v_readlane_b32 s5, v255, 18
	s_add_u32 s0, s4, s0
	v_add_f32_e32 v0, v40, v0
	s_addc_u32 s1, s5, 0
	v_lshlrev_b32_e32 v35, 2, v93
	v_add_f32_e32 v0, v41, v0
	global_load_dwordx4 v[40:43], v35, s[0:1] offset:2048
	global_load_dwordx4 v[44:47], v35, s[0:1] offset:2176
	global_load_dwordx4 v[48:51], v35, s[0:1] offset:2080
	global_load_dwordx4 v[52:55], v35, s[0:1] offset:2208
	global_load_dwordx4 v[56:59], v35, s[0:1] offset:2112
	global_load_dwordx4 v[60:63], v35, s[0:1] offset:2240
	global_load_dwordx4 v[64:67], v35, s[0:1] offset:2144
	global_load_dwordx4 v[68:71], v35, s[0:1] offset:2272
	v_mov_b32_e32 v34, v0
	s_nop 1
	v_permlane32_swap_b32_e32 v0, v34
	v_add_f32_e32 v0, v0, v34
	v_fmamk_f32 v0, v0, 0x3c800000, v139
	v_cmp_gt_f32_e32 vcc, s71, v0
	v_mul_f32_e32 v34, 0x4b800000, v0
	s_mov_b32 s17, s31
	v_cndmask_b32_e32 v0, v0, v34, vcc
	v_rsq_f32_e32 v0, v0
	v_lshl_add_u64 v[36:37], v[90:91], 0, s[16:17]
	v_readlane_b32 s4, v253, 25
	v_lshlrev_b64 v[36:37], 11, v[36:37]
	v_mul_f32_e32 v34, 0x45800000, v0
	v_cndmask_b32_e32 v34, v0, v34, vcc
	v_readlane_b32 s5, v253, 26
	v_pk_mul_f32 v[18:19], v[18:19], v[34:35] op_sel_hi:[1,0]
	v_lshlrev_b32_e32 v0, 1, v93
	v_lshl_add_u64 v[36:37], s[4:5], 0, v[36:37]
	v_lshl_add_u64 v[38:39], v[36:37], 0, s[30:31]
	v_pk_mul_f32 v[2:3], v[2:3], v[34:35] op_sel_hi:[1,0]
	v_pk_mul_f32 v[4:5], v[4:5], v[34:35] op_sel_hi:[1,0]
	v_pk_mul_f32 v[6:7], v[6:7], v[34:35] op_sel_hi:[1,0]
	v_readlane_b32 s18, v253, 53
	s_mov_b32 s19, 0x3fb8aa3b
	s_movk_i32 s27, 0x280
	s_mov_b32 s30, 0x3f200000
	s_waitcnt vmcnt(0)
	v_pk_mul_f32 v[18:19], v[40:41], v[18:19]
	s_nop 0
	v_cvt_pk_bf16_f32 v36, v18, v19
	v_pk_mul_f32 v[18:19], v[20:21], v[34:35] op_sel_hi:[1,0]
	v_pk_mul_f32 v[20:21], v[22:23], v[34:35] op_sel_hi:[1,0]
	v_pk_mul_f32 v[18:19], v[42:43], v[18:19]
	s_nop 0
	v_cvt_pk_bf16_f32 v37, v18, v19
	v_lshl_add_u64 v[18:19], v[38:39], 0, v[0:1]
	global_store_dwordx2 v[18:19], v[36:37], off offset:1024
	v_pk_mul_f32 v[2:3], v[44:45], v[2:3]
	v_pk_mul_f32 v[4:5], v[46:47], v[4:5]
	v_cvt_pk_bf16_f32 v2, v2, v3
	v_cvt_pk_bf16_f32 v3, v4, v5
	global_store_dwordx2 v[18:19], v[2:3], off offset:1088
	v_pk_mul_f32 v[2:3], v[20:21], v[48:49]
	v_pk_mul_f32 v[20:21], v[24:25], v[34:35] op_sel_hi:[1,0]
	v_cvt_pk_bf16_f32 v2, v2, v3
	v_pk_mul_f32 v[4:5], v[20:21], v[50:51]
	s_nop 0
	v_cvt_pk_bf16_f32 v3, v4, v5
	global_store_dwordx2 v[18:19], v[2:3], off offset:1040
	v_pk_mul_f32 v[2:3], v[6:7], v[52:53]
	v_pk_mul_f32 v[6:7], v[8:9], v[34:35] op_sel_hi:[1,0]
	v_cvt_pk_bf16_f32 v2, v2, v3
	v_pk_mul_f32 v[4:5], v[6:7], v[54:55]
	v_pk_mul_f32 v[6:7], v[26:27], v[34:35] op_sel_hi:[1,0]
	v_cvt_pk_bf16_f32 v3, v4, v5
	global_store_dwordx2 v[18:19], v[2:3], off offset:1104
	v_pk_mul_f32 v[2:3], v[6:7], v[56:57]
	v_pk_mul_f32 v[6:7], v[28:29], v[34:35] op_sel_hi:[1,0]
	v_cvt_pk_bf16_f32 v2, v2, v3
	v_pk_mul_f32 v[4:5], v[6:7], v[58:59]
	v_pk_mul_f32 v[6:7], v[10:11], v[34:35] op_sel_hi:[1,0]
	v_cvt_pk_bf16_f32 v3, v4, v5
	global_store_dwordx2 v[18:19], v[2:3], off offset:1056
	v_pk_mul_f32 v[2:3], v[6:7], v[60:61]
	v_pk_mul_f32 v[6:7], v[12:13], v[34:35] op_sel_hi:[1,0]
	v_cvt_pk_bf16_f32 v2, v2, v3
	v_pk_mul_f32 v[4:5], v[6:7], v[62:63]
	v_pk_mul_f32 v[6:7], v[30:31], v[34:35] op_sel_hi:[1,0]
	v_cvt_pk_bf16_f32 v3, v4, v5
	global_store_dwordx2 v[18:19], v[2:3], off offset:1120
	v_pk_mul_f32 v[2:3], v[6:7], v[64:65]
	v_pk_mul_f32 v[6:7], v[32:33], v[34:35] op_sel_hi:[1,0]
	v_cvt_pk_bf16_f32 v2, v2, v3
	v_pk_mul_f32 v[4:5], v[6:7], v[66:67]
	v_pk_mul_f32 v[6:7], v[14:15], v[34:35] op_sel_hi:[1,0]
	v_cvt_pk_bf16_f32 v3, v4, v5
	global_store_dwordx2 v[18:19], v[2:3], off offset:1072
	v_pk_mul_f32 v[2:3], v[6:7], v[68:69]
	v_pk_mul_f32 v[6:7], v[16:17], v[34:35] op_sel_hi:[1,0]
	v_cvt_pk_bf16_f32 v2, v2, v3
	v_pk_mul_f32 v[4:5], v[6:7], v[70:71]
	s_nop 0
	v_cvt_pk_bf16_f32 v3, v4, v5
	global_store_dwordx2 v[18:19], v[2:3], off offset:1136
	s_waitcnt lgkmcnt(0)
	s_barrier

; #define LAS __attribute__((address_space(3)))
; #define MFMA32(a, b, c) __builtin_amdgcn_mfma_f32_32x32x16_bf16((a), (b), (c), 0, 0, 0)
; __device__ __forceinline__ int crow(int i, int h) { return (i & 3) + 8 * (i >> 2) + 4 * h; }
; template <int MODE, class SF> ...
;     f32x16 s0, s1;
; #pragma unroll
;     for (int i = 0; i < 16; ++i) { s0[i] = 0.f; s1[i] = 0.f; }
;     bf16x8 ka[4], kb2[4];
; #pragma unroll
;     for (int s = 0; s < 4; ++s) { ka[s] = *(LAS const bf16x8*)(ksb + r * KSB + (16 * s + 8 * hh) * 2); kb2[s] = *(LAS const bf16x8*)(ksb + (32 + r) * KSB + (16 * s + 8 * hh) * 2); }
;     __builtin_amdgcn_s_setprio(1);
; #pragma unroll
;     for (int s = 0; s < 4; ++s) { s0 = MFMA32(ka[s], qf[s], s0); s1 = MFMA32(kb2[s], qf[s], s1); }
;     __builtin_amdgcn_s_setprio(0);
;     __builtin_amdgcn_sched_barrier(0);
; #pragma unroll
;     for (int i = 0; i < 16; ++i) { s0[i] = sf(s0[i], crow(i, hh)); s1[i] = sf(s1[i], 32 + crow(i, hh)); }
.LBB0_1293:
	v_lshrrev_b64 v[34:35], s8, v[108:109]
	v_and_b32_e32 v0, 1, v34
	v_cmp_eq_u32_e64 s[0:1], 1, v0
	v_cmp_ne_u32_e32 vcc, 0, v0
	s_cbranch_vccz .LBB0_1301
	s_lshl_b32 s24, s8, 6
	s_cmp_le_u32 s19, s8
	s_mov_b64 s[8:9], -1
	v_add3_u32 v115, s25, v150, v104
	s_cbranch_scc0 .LBB0_1298
	ds_read_b128 v[34:37], v115
	ds_read_b128 v[116:119], v115 offset:32
	ds_read_b128 v[38:41], v115 offset:4608
	ds_read_b128 v[120:123], v115 offset:4640
	ds_read_b128 v[124:127], v115 offset:64
	ds_read_b128 v[128:131], v115 offset:96
	ds_read_b128 v[186:189], v115 offset:4672
	ds_read_b128 v[190:193], v115 offset:4704
	s_setprio 1
	s_waitcnt lgkmcnt(7)
	v_mfma_f32_32x32x16_bf16 v[50:65], v[34:37], v[74:77], 0
	s_waitcnt lgkmcnt(5)
	v_mfma_f32_32x32x16_bf16 v[34:49], v[38:41], v[74:77], 0
	v_mfma_f32_32x32x16_bf16 v[50:65], v[116:119], v[70:73], v[50:65]
	s_waitcnt lgkmcnt(4)
	v_mfma_f32_32x32x16_bf16 v[34:49], v[120:123], v[70:73], v[34:49]
	s_waitcnt lgkmcnt(3)
	v_mfma_f32_32x32x16_bf16 v[50:65], v[124:127], v[66:69], v[50:65]
	s_waitcnt lgkmcnt(1)
	v_mfma_f32_32x32x16_bf16 v[34:49], v[186:189], v[66:69], v[34:49]
	v_mfma_f32_32x32x16_bf16 v[50:65], v[128:131], v[78:81], v[50:65]
	s_waitcnt lgkmcnt(0)
	v_mfma_f32_32x32x16_bf16 v[34:49], v[190:193], v[78:81], v[34:49]
	s_setprio 0
	v_or_b32_e32 v0, s24, v133
	v_sub_u32_e32 v116, v102, v0
	v_cvt_f32_i32_e32 v116, v116
	v_or_b32_e32 v117, s24, v154
	v_sub_u32_e32 v118, v102, v117
	v_cvt_f32_i32_e32 v118, v118
	v_cmp_ge_i32_e32 vcc, v102, v0
	s_nop 1
	v_fma_f32 v50, -v105, v116, v50
	s_and_b64 vcc, s[0:1], vcc
	v_cndmask_b32_e32 v50, v215, v50, vcc
	v_cmp_ge_i32_e32 vcc, v102, v117
	v_fma_f32 v34, -v105, v118, v34
	s_and_b64 vcc, s[0:1], vcc
	v_cndmask_b32_e32 v34, v215, v34, vcc
	v_cmp_gt_i32_e32 vcc, v102, v0
	v_xad_u32 v0, v0, -1, v102
	v_or_b32_e32 v116, s24, v155
	v_cvt_f32_i32_e32 v0, v0
	v_sub_u32_e32 v117, v102, v116
	v_cvt_f32_i32_e32 v117, v117
	s_and_b64 vcc, s[0:1], vcc
	v_fma_f32 v0, -v105, v0, v51
	v_or_b32_e32 v51, s24, v156
	v_fma_f32 v35, -v105, v117, v35
	v_sub_u32_e32 v117, v102, v51
	v_cvt_f32_i32_e32 v117, v117
	v_cndmask_b32_e32 v0, v215, v0, vcc
	v_cmp_ge_i32_e32 vcc, v102, v116
	v_or_b32_e32 v116, s24, v157
	v_fma_f32 v52, -v105, v117, v52
	v_sub_u32_e32 v117, v102, v116
	s_and_b64 vcc, s[0:1], vcc
	v_cvt_f32_i32_e32 v117, v117
	v_cndmask_b32_e32 v35, v215, v35, vcc
	v_cmp_ge_i32_e32 vcc, v102, v51
	s_and_b64 vcc, s[0:1], vcc
	v_fma_f32 v36, -v105, v117, v36
	v_cndmask_b32_e32 v51, v215, v52, vcc
	v_or_b32_e32 v52, s24, v158
	v_sub_u32_e32 v117, v102, v52
	v_cvt_f32_i32_e32 v117, v117
	v_cmp_ge_i32_e32 vcc, v102, v116
	v_or_b32_e32 v116, s24, v159
	s_and_b64 vcc, s[0:1], vcc
	v_fma_f32 v53, -v105, v117, v53
	v_sub_u32_e32 v117, v102, v116
	v_cvt_f32_i32_e32 v117, v117
	v_cndmask_b32_e32 v36, v215, v36, vcc
	v_cmp_ge_i32_e32 vcc, v102, v52
	s_and_b64 vcc, s[0:1], vcc
	v_fma_f32 v37, -v105, v117, v37
	v_cndmask_b32_e32 v52, v215, v53, vcc
	v_or_b32_e32 v53, s24, v160
	v_sub_u32_e32 v117, v102, v53
	v_cvt_f32_i32_e32 v117, v117
	v_cmp_ge_i32_e32 vcc, v102, v116
	v_or_b32_e32 v116, s24, v161
	s_and_b64 vcc, s[0:1], vcc
	v_fma_f32 v54, -v105, v117, v54
	v_sub_u32_e32 v117, v102, v116
	v_cvt_f32_i32_e32 v117, v117
	v_cndmask_b32_e32 v37, v215, v37, vcc
	v_cmp_ge_i32_e32 vcc, v102, v53
	s_and_b64 vcc, s[0:1], vcc
	v_fma_f32 v38, -v105, v117, v38
	v_cndmask_b32_e32 v53, v215, v54, vcc
	v_or_b32_e32 v54, s24, v162
	v_sub_u32_e32 v117, v102, v54
	v_cvt_f32_i32_e32 v117, v117
	v_cmp_ge_i32_e32 vcc, v102, v116
	v_or_b32_e32 v116, s24, v163
	s_and_b64 vcc, s[0:1], vcc
	v_fma_f32 v55, -v105, v117, v55
	v_sub_u32_e32 v117, v102, v116
	v_cvt_f32_i32_e32 v117, v117
	v_cndmask_b32_e32 v38, v215, v38, vcc
	v_cmp_ge_i32_e32 vcc, v102, v54
	s_and_b64 vcc, s[0:1], vcc
	v_fma_f32 v39, -v105, v117, v39
	v_cndmask_b32_e32 v54, v215, v55, vcc
	v_or_b32_e32 v55, s24, v164
	v_sub_u32_e32 v117, v102, v55
	v_cvt_f32_i32_e32 v117, v117
	v_cmp_ge_i32_e32 vcc, v102, v116
	v_or_b32_e32 v116, s24, v165
	s_and_b64 vcc, s[0:1], vcc
	v_fma_f32 v56, -v105, v117, v56
	v_sub_u32_e32 v117, v102, v116
	v_cvt_f32_i32_e32 v117, v117
	v_cndmask_b32_e32 v39, v215, v39, vcc
	v_cmp_ge_i32_e32 vcc, v102, v55
	s_and_b64 vcc, s[0:1], vcc
	v_fma_f32 v40, -v105, v117, v40
	v_cndmask_b32_e32 v55, v215, v56, vcc
	v_or_b32_e32 v56, s24, v166
	v_sub_u32_e32 v117, v102, v56
	v_cvt_f32_i32_e32 v117, v117
	v_cmp_ge_i32_e32 vcc, v102, v116
	v_or_b32_e32 v116, s24, v167
	s_and_b64 vcc, s[0:1], vcc
	v_fma_f32 v57, -v105, v117, v57
	v_sub_u32_e32 v117, v102, v116
	v_cvt_f32_i32_e32 v117, v117
	v_cndmask_b32_e32 v40, v215, v40, vcc
	v_cmp_ge_i32_e32 vcc, v102, v56
	s_and_b64 vcc, s[0:1], vcc
	v_fma_f32 v41, -v105, v117, v41
	v_cndmask_b32_e32 v56, v215, v57, vcc
	v_or_b32_e32 v57, s24, v168
	v_sub_u32_e32 v117, v102, v57
	v_cvt_f32_i32_e32 v117, v117
	v_cmp_ge_i32_e32 vcc, v102, v116
	v_or_b32_e32 v116, s24, v169
	s_and_b64 vcc, s[0:1], vcc
	v_fma_f32 v58, -v105, v117, v58
	v_sub_u32_e32 v117, v102, v116
	v_cvt_f32_i32_e32 v117, v117
	v_cndmask_b32_e32 v41, v215, v41, vcc
	v_cmp_ge_i32_e32 vcc, v102, v57
	s_and_b64 vcc, s[0:1], vcc
	v_fma_f32 v42, -v105, v117, v42
	v_cndmask_b32_e32 v57, v215, v58, vcc
	v_or_b32_e32 v58, s24, v170
	v_sub_u32_e32 v117, v102, v58
	v_cvt_f32_i32_e32 v117, v117
	v_cmp_ge_i32_e32 vcc, v102, v116
	v_or_b32_e32 v116, s24, v171
	s_and_b64 vcc, s[0:1], vcc
	v_fma_f32 v59, -v105, v117, v59
	v_sub_u32_e32 v117, v102, v116
	v_cvt_f32_i32_e32 v117, v117
	v_cndmask_b32_e32 v42, v215, v42, vcc
	v_cmp_ge_i32_e32 vcc, v102, v58
	s_and_b64 vcc, s[0:1], vcc
	v_fma_f32 v43, -v105, v117, v43
	v_cndmask_b32_e32 v58, v215, v59, vcc
; __device__ __forceinline__ float sum32(float v) { auto rr = __builtin_amdgcn_permlane32_swap(__float_as_uint(v), __float_as_uint(v), false, false); return __uint_as_float(rr[0]) + __uint_as_float(rr[1]); }
; __device__ __forceinline__ float max32(float v) { auto rr = __builtin_amdgcn_permlane32_swap(__float_as_uint(v), __float_as_uint(v), false, false); return fmaxf(__uint_as_float(rr[0]), __uint_as_float(rr[1])); }
; #define EXP2(x) __builtin_amdgcn_exp2f(x)
; template <int MODE, class SF> ...
;     ...
;     if (MODE != 2) {
;         float mloc = fmaxf(s0[0], s1[0]);
; #pragma unroll
;         for (int i = 1; i < 16; ++i) mloc = fmaxf(mloc, fmaxf(s0[i], s1[i]));
;         mloc = max32(mloc);
;         const float mnew = fmaxf(m, mloc), msafe = mnew == -INFINITY ? 0.f : mnew, corr = EXP2(m - msafe);
;         float psum = 0.f;
; #pragma unroll
;         for (int i = 0; i < 16; ++i) { s0[i] = EXP2(s0[i] - msafe); s1[i] = EXP2(s1[i] - msafe); psum += s0[i] + s1[i]; }
;         psum = sum32(psum);
;         l = l * corr + psum; m = mnew;
;         if (MODE == 0 && !__all(corr == 1.f)) {
; #pragma unroll
;             for (int i = 0; i < 16; ++i) { o0[i] *= corr; o1[i] *= corr; } }
	v_or_b32_e32 v59, s24, v172
	v_sub_u32_e32 v117, v102, v59
	v_cvt_f32_i32_e32 v117, v117
	v_cmp_ge_i32_e32 vcc, v102, v116
	v_or_b32_e32 v116, s24, v173
	s_and_b64 vcc, s[0:1], vcc
	v_fma_f32 v60, -v105, v117, v60
	v_sub_u32_e32 v117, v102, v116
	v_cvt_f32_i32_e32 v117, v117
	v_cndmask_b32_e32 v43, v215, v43, vcc
	v_cmp_ge_i32_e32 vcc, v102, v59
	s_and_b64 vcc, s[0:1], vcc
	v_fma_f32 v44, -v105, v117, v44
	v_cndmask_b32_e32 v59, v215, v60, vcc
	v_or_b32_e32 v60, s24, v174
	v_sub_u32_e32 v117, v102, v60
	v_cvt_f32_i32_e32 v117, v117
	v_cmp_ge_i32_e32 vcc, v102, v116
	v_or_b32_e32 v116, s24, v175
	s_and_b64 vcc, s[0:1], vcc
	v_fma_f32 v61, -v105, v117, v61
	v_sub_u32_e32 v117, v102, v116
	v_cvt_f32_i32_e32 v117, v117
	v_cndmask_b32_e32 v44, v215, v44, vcc
	v_cmp_ge_i32_e32 vcc, v102, v60
	s_and_b64 vcc, s[0:1], vcc
	v_fma_f32 v45, -v105, v117, v45
	v_cndmask_b32_e32 v60, v215, v61, vcc
	v_or_b32_e32 v61, s24, v176
	v_sub_u32_e32 v117, v102, v61
	v_cvt_f32_i32_e32 v117, v117
	v_cmp_ge_i32_e32 vcc, v102, v116
	v_or_b32_e32 v116, s24, v177
	s_and_b64 vcc, s[0:1], vcc
	v_fma_f32 v62, -v105, v117, v62
	v_sub_u32_e32 v117, v102, v116
	v_cvt_f32_i32_e32 v117, v117
	v_cndmask_b32_e32 v45, v215, v45, vcc
	v_cmp_ge_i32_e32 vcc, v102, v61
	s_and_b64 vcc, s[0:1], vcc
	v_fma_f32 v46, -v105, v117, v46
	v_cndmask_b32_e32 v61, v215, v62, vcc
	v_or_b32_e32 v62, s24, v178
	v_sub_u32_e32 v117, v102, v62
	v_cvt_f32_i32_e32 v117, v117
	v_cmp_ge_i32_e32 vcc, v102, v116
	v_or_b32_e32 v116, s24, v179
	s_and_b64 vcc, s[0:1], vcc
	v_fma_f32 v63, -v105, v117, v63
	v_sub_u32_e32 v117, v102, v116
	v_cvt_f32_i32_e32 v117, v117
	v_cndmask_b32_e32 v46, v215, v46, vcc
	v_cmp_ge_i32_e32 vcc, v102, v62
	s_and_b64 vcc, s[0:1], vcc
	v_fma_f32 v47, -v105, v117, v47
	v_cndmask_b32_e32 v62, v215, v63, vcc
	v_or_b32_e32 v63, s24, v180
	v_sub_u32_e32 v117, v102, v63
	v_cvt_f32_i32_e32 v117, v117
	v_cmp_ge_i32_e32 vcc, v102, v116
	v_or_b32_e32 v116, s24, v181
	s_and_b64 vcc, s[0:1], vcc
	v_fma_f32 v64, -v105, v117, v64
	v_sub_u32_e32 v117, v102, v116
	v_cvt_f32_i32_e32 v117, v117
	v_cndmask_b32_e32 v47, v215, v47, vcc
	v_cmp_ge_i32_e32 vcc, v102, v63
	s_and_b64 vcc, s[0:1], vcc
	v_fma_f32 v48, -v105, v117, v48
	v_cndmask_b32_e32 v63, v215, v64, vcc
	v_or_b32_e32 v64, s24, v182
	v_sub_u32_e32 v117, v102, v64
	v_cvt_f32_i32_e32 v117, v117
	v_cmp_ge_i32_e32 vcc, v102, v116
	v_or_b32_e32 v116, s24, v183
	s_and_b64 vcc, s[0:1], vcc
	v_fma_f32 v65, -v105, v117, v65
	v_sub_u32_e32 v117, v102, v116
	v_cvt_f32_i32_e32 v117, v117
	v_cndmask_b32_e32 v48, v215, v48, vcc
	v_cmp_ge_i32_e32 vcc, v102, v64
	s_and_b64 vcc, s[0:1], vcc
	v_fma_f32 v49, -v105, v117, v49
	v_cndmask_b32_e32 v64, v215, v65, vcc
	v_max_f32_e32 v65, v0, v35
	v_cmp_ge_i32_e32 vcc, v102, v116
	v_max3_f32 v65, v50, v34, v65
	v_max_f32_e32 v116, v51, v36
	v_max_f32_e32 v117, v52, v37
	v_max3_f32 v65, v65, v116, v117
	v_max_f32_e32 v116, v53, v38
	v_max_f32_e32 v117, v54, v39
	v_max3_f32 v65, v65, v116, v117
	v_max_f32_e32 v116, v55, v40
	v_max_f32_e32 v117, v56, v41
	v_max3_f32 v65, v65, v116, v117
	v_max_f32_e32 v116, v57, v42
	v_max_f32_e32 v117, v58, v43
	s_and_b64 vcc, s[0:1], vcc
	v_max3_f32 v65, v65, v116, v117
	v_max_f32_e32 v116, v59, v44
	v_max_f32_e32 v117, v60, v45
	v_cndmask_b32_e32 v49, v215, v49, vcc
	v_max3_f32 v65, v65, v116, v117
	v_max_f32_e32 v116, v61, v46
	v_max_f32_e32 v117, v62, v47
	v_max3_f32 v65, v65, v116, v117
	v_max_f32_e32 v116, v63, v48
	v_max_f32_e32 v117, v64, v49
	v_max3_f32 v65, v65, v116, v117
	v_mov_b32_e32 v116, v65
	s_nop 1
	v_permlane32_swap_b32_e32 v65, v116
	v_max3_f32 v185, v114, v65, v116
	v_cmp_neq_f32_e32 vcc, s34, v185
	s_nop 1
	v_cndmask_b32_e32 v65, 0, v185, vcc
	v_sub_f32_e32 v36, v36, v65
	v_exp_f32_e32 v119, v36
	v_sub_f32_e32 v36, v52, v65
	v_exp_f32_e32 v189, v36
	v_sub_f32_e32 v36, v37, v65
	v_exp_f32_e32 v120, v36
	v_sub_f32_e32 v36, v53, v65
	v_exp_f32_e32 v191, v36
	v_sub_f32_e32 v36, v38, v65
	v_exp_f32_e32 v121, v36
	v_sub_f32_e32 v36, v54, v65
	v_exp_f32_e32 v193, v36
	v_sub_f32_e32 v36, v39, v65
	v_exp_f32_e32 v123, v36
	v_sub_f32_e32 v36, v55, v65
	v_exp_f32_e32 v195, v36
	v_sub_f32_e32 v36, v40, v65
	v_exp_f32_e32 v125, v36
	v_sub_f32_e32 v36, v56, v65
	v_exp_f32_e32 v197, v36
	v_sub_f32_e32 v36, v41, v65
	v_sub_f32_e32 v50, v50, v65
	v_sub_f32_e32 v34, v34, v65
	v_sub_f32_e32 v0, v0, v65
	v_exp_f32_e32 v127, v36
	v_sub_f32_e32 v36, v57, v65
	v_exp_f32_e32 v129, v50
	v_exp_f32_e32 v116, v34
	v_exp_f32_e32 v131, v0
	v_sub_f32_e32 v0, v35, v65
	v_exp_f32_e32 v192, v36
	v_sub_f32_e32 v36, v42, v65
	v_exp_f32_e32 v118, v0
	v_sub_f32_e32 v50, v51, v65
	v_exp_f32_e32 v122, v36
	v_sub_f32_e32 v36, v58, v65
	v_exp_f32_e32 v187, v50
	v_exp_f32_e32 v194, v36
	v_sub_f32_e32 v36, v43, v65
	v_exp_f32_e32 v124, v36
	v_sub_f32_e32 v36, v59, v65
	v_add_f32_e32 v34, v129, v116
	v_exp_f32_e32 v196, v36
	v_sub_f32_e32 v36, v44, v65
	v_add_f32_e32 v34, 0, v34
	v_add_f32_e32 v35, v131, v118
	v_exp_f32_e32 v126, v36
	v_sub_f32_e32 v36, v60, v65
	v_add_f32_e32 v34, v35, v34
	v_add_f32_e32 v35, v187, v119
	v_exp_f32_e32 v198, v36
	v_sub_f32_e32 v36, v45, v65
	v_add_f32_e32 v34, v35, v34
	v_add_f32_e32 v35, v189, v120
	v_exp_f32_e32 v128, v36
	v_sub_f32_e32 v36, v61, v65
	v_add_f32_e32 v34, v35, v34
	v_add_f32_e32 v35, v191, v121
	v_exp_f32_e32 v199, v36
	v_sub_f32_e32 v36, v46, v65
	v_add_f32_e32 v34, v35, v34
	v_add_f32_e32 v35, v193, v123
	v_exp_f32_e32 v130, v36
	v_sub_f32_e32 v36, v62, v65
	v_add_f32_e32 v34, v35, v34
	v_add_f32_e32 v35, v195, v125
	v_exp_f32_e32 v200, v36
	v_sub_f32_e32 v36, v47, v65
	v_add_f32_e32 v34, v35, v34
	v_add_f32_e32 v35, v197, v127
	v_exp_f32_e32 v186, v36
	v_sub_f32_e32 v36, v63, v65
	v_add_f32_e32 v34, v35, v34
	v_add_f32_e32 v35, v192, v122
	v_exp_f32_e32 v201, v36
	v_sub_f32_e32 v36, v48, v65
	v_add_f32_e32 v34, v35, v34
	v_add_f32_e32 v35, v194, v124
	v_exp_f32_e32 v188, v36
	v_sub_f32_e32 v36, v64, v65
	v_add_f32_e32 v34, v35, v34
	v_add_f32_e32 v35, v196, v126
	v_exp_f32_e32 v202, v36
	v_sub_f32_e32 v36, v49, v65
	v_add_f32_e32 v34, v35, v34
	v_add_f32_e32 v35, v198, v128
	v_exp_f32_e32 v190, v36
	v_sub_f32_e32 v0, v114, v65
	v_add_f32_e32 v34, v35, v34
	v_add_f32_e32 v35, v199, v130
	v_add_f32_e32 v34, v35, v34
	v_add_f32_e32 v35, v200, v186
	v_exp_f32_e32 v0, v0
	v_add_f32_e32 v34, v35, v34
	v_add_f32_e32 v35, v201, v188
	v_add_f32_e32 v34, v35, v34
	v_add_f32_e32 v35, v202, v190
	v_add_f32_e32 v117, v35, v34
	v_mov_b32_e32 v203, v117
	v_cmp_eq_f32_e32 vcc, 1.0, v0
	v_permlane32_swap_b32_e32 v117, v203
	s_cmp_eq_u64 vcc, exec
	s_cbranch_scc1 .LBB0_1297
; #define LAS __attribute__((address_space(3)))
; __device__ __forceinline__ void pv_accum(const f32x16& s0, const f32x16& s1, f32x16& o0, f32x16& o1, LAS const unsigned char* vtb, int r, int hh) {
;     __builtin_amdgcn_s_setprio(1);
; #pragma unroll
;     for (int kt = 0; kt < 2; ++kt)
; #pragma unroll
;         for (int sp = 0; sp < 2; ++sp) { u32x4 w;
;             if (kt == 0) { w.x = cvtpk(s0[8 * sp], s0[8 * sp + 1]); w.y = cvtpk(s0[8 * sp + 2], s0[8 * sp + 3]); w.z = cvtpk(s0[8 * sp + 4], s0[8 * sp + 5]); w.w = cvtpk(s0[8 * sp + 6], s0[8 * sp + 7]); }
;             else         { w.x = cvtpk(s1[8 * sp], s1[8 * sp + 1]); w.y = cvtpk(s1[8 * sp + 2], s1[8 * sp + 3]); w.z = cvtpk(s1[8 * sp + 4], s1[8 * sp + 5]); w.w = cvtpk(s1[8 * sp + 6], s1[8 * sp + 7]); }
;             const bf16x8 pb = __builtin_bit_cast(bf16x8, w); const int ko = 32 * kt + 16 * sp + 4 * hh;
;             { const s16x4 lo = *(LAS const s16x4*)(vtb + r * VTB + ko * 2), hi = *(LAS const s16x4*)(vtb + r * VTB + (ko + 8) * 2);
;               o0 = MFMA32(__builtin_shufflevector(lo, hi, 0, 1, 2, 3, 4, 5, 6, 7), pb, o0); }
;             { const s16x4 lo = *(LAS const s16x4*)(vtb + (32 + r) * VTB + ko * 2), hi = *(LAS const s16x4*)(vtb + (32 + r) * VTB + (ko + 8) * 2);
;               o1 = MFMA32(__builtin_shufflevector(lo, hi, 0, 1, 2, 3, 4, 5, 6, 7), pb, o1); } }
;     __builtin_amdgcn_s_setprio(0);
; }
; __device__ __forceinline__ void attn_block_full(const bf16x8 (&qf)[4], f32x16& o0, f32x16& o1, float& m, float& l, LAS const unsigned char* ksb, LAS const unsigned char* vtb, int r, int hh, float b0, float sl) {
;     f32x16 s0, s1;
; #pragma unroll
;     for (int i = 0; i < 16; ++i) { s0[i] = 0.f; s1[i] = 0.f; }
;     bf16x8 ka[4], kb2[4];
; #pragma unroll
;     for (int s = 0; s < 4; ++s) { ka[s] = *(LAS const bf16x8*)(ksb + r * KSB + (16 * s + 8 * hh) * 2); kb2[s] = *(LAS const bf16x8*)(ksb + (32 + r) * KSB + (16 * s + 8 * hh) * 2); }
;     __builtin_amdgcn_s_setprio(1);
; #pragma unroll
;     for (int s = 0; s < 4; ++s) { s0 = MFMA32(ka[s], qf[s], s0); s1 = MFMA32(kb2[s], qf[s], s1); }
;     __builtin_amdgcn_s_setprio(0);
;     __builtin_amdgcn_sched_barrier(0);
; #pragma unroll
;     for (int i = 0; i < 16; ++i) { const float c = (float)((i & 3) + 8 * (i >> 2)); s0[i] = fmaf(sl, c, s0[i]); s1[i] = fmaf(sl, c + 32.f, s1[i]); }
;     float mloc = fmaxf(s0[0], s1[0]);
; #pragma unroll
	v_pk_mul_f32 v[32:33], v[32:33], v[0:1] op_sel_hi:[1,0]
	v_pk_mul_f32 v[30:31], v[30:31], v[0:1] op_sel_hi:[1,0]
	v_pk_mul_f32 v[28:29], v[28:29], v[0:1] op_sel_hi:[1,0]
	v_pk_mul_f32 v[26:27], v[26:27], v[0:1] op_sel_hi:[1,0]
	v_pk_mul_f32 v[24:25], v[24:25], v[0:1] op_sel_hi:[1,0]
	v_pk_mul_f32 v[22:23], v[22:23], v[0:1] op_sel_hi:[1,0]
	v_pk_mul_f32 v[20:21], v[20:21], v[0:1] op_sel_hi:[1,0]
	v_pk_mul_f32 v[18:19], v[18:19], v[0:1] op_sel_hi:[1,0]
	v_pk_mul_f32 v[16:17], v[16:17], v[0:1] op_sel_hi:[1,0]
	v_pk_mul_f32 v[14:15], v[14:15], v[0:1] op_sel_hi:[1,0]
	v_pk_mul_f32 v[12:13], v[12:13], v[0:1] op_sel_hi:[1,0]
	v_pk_mul_f32 v[10:11], v[10:11], v[0:1] op_sel_hi:[1,0]
	v_pk_mul_f32 v[8:9], v[8:9], v[0:1] op_sel_hi:[1,0]
	v_pk_mul_f32 v[6:7], v[6:7], v[0:1] op_sel_hi:[1,0]
	v_pk_mul_f32 v[4:5], v[4:5], v[0:1] op_sel_hi:[1,0]
	v_pk_mul_f32 v[2:3], v[2:3], v[0:1] op_sel_hi:[1,0]
.LBB0_1297:
	v_add_f32_e32 v117, v117, v203
	v_fmac_f32_e32 v117, v184, v0
	s_setprio 1
	v_add3_u32 v0, s44, v151, v132
	v_add_u32_e32 v140, 0x4800, v0
	ds_read2_b64 v[204:207], v140 offset1:2
	v_cvt_pk_bf16_f32 v220, v129, v131
	v_cvt_pk_bf16_f32 v221, v187, v189
	v_cvt_pk_bf16_f32 v222, v191, v193
	v_cvt_pk_bf16_f32 v223, v195, v197
	v_add_u32_e32 v0, 0x5800, v0
	v_cvt_pk_bf16_f32 v192, v192, v194
	v_cvt_pk_bf16_f32 v193, v196, v198
	v_cvt_pk_bf16_f32 v194, v199, v200
	s_waitcnt lgkmcnt(0)
	v_mfma_f32_32x32x16_bf16 v[18:33], v[204:207], v[220:223], v[18:33]
	ds_read2_b64 v[204:207], v0 offset0:32 offset1:34
	ds_read2_b64 v[196:199], v0 offset0:36 offset1:38
	v_cvt_pk_bf16_f32 v195, v201, v202
	v_cvt_pk_bf16_f32 v118, v116, v118
	v_cvt_pk_bf16_f32 v119, v119, v120
	v_cvt_pk_bf16_f32 v120, v121, v123
	v_cvt_pk_bf16_f32 v121, v125, v127
	v_cvt_pk_bf16_f32 v122, v122, v124
	s_waitcnt lgkmcnt(1)
	v_mfma_f32_32x32x16_bf16 v[2:17], v[204:207], v[220:223], v[2:17]
	ds_read2_b64 v[204:207], v140 offset0:4 offset1:6
	v_cvt_pk_bf16_f32 v123, v126, v128
	v_cvt_pk_bf16_f32 v124, v130, v186
	v_cvt_pk_bf16_f32 v125, v188, v190
	s_mov_b64 s[8:9], 0
	s_waitcnt lgkmcnt(0)
	v_mfma_f32_32x32x16_bf16 v[18:33], v[204:207], v[192:195], v[18:33]
	v_mfma_f32_32x32x16_bf16 v[2:17], v[196:199], v[192:195], v[2:17]
	ds_read2_b64 v[192:195], v140 offset0:8 offset1:10
	s_waitcnt lgkmcnt(0)
	v_mfma_f32_32x32x16_bf16 v[18:33], v[192:195], v[118:121], v[18:33]
	ds_read2_b64 v[192:195], v0 offset0:40 offset1:42
	s_waitcnt lgkmcnt(0)
	v_mfma_f32_32x32x16_bf16 v[2:17], v[192:195], v[118:121], v[2:17]
	ds_read2_b64 v[118:121], v140 offset0:12 offset1:14
	s_waitcnt lgkmcnt(0)
	v_mfma_f32_32x32x16_bf16 v[18:33], v[118:121], v[122:125], v[18:33]
	ds_read2_b64 v[118:121], v0 offset0:44 offset1:46
	s_waitcnt lgkmcnt(0)
	v_mfma_f32_32x32x16_bf16 v[2:17], v[118:121], v[122:125], v[2:17]
.LBB0_1298:
	s_and_b64 vcc, exec, s[8:9]
	s_cbranch_vccz .LBB0_1300
	s_nop 6
	ds_read_b128 v[34:37], v115
	ds_read_b128 v[116:119], v115 offset:32
	ds_read_b128 v[38:41], v115 offset:4608
	ds_read_b128 v[120:123], v115 offset:4640
	ds_read_b128 v[124:127], v115 offset:64
	ds_read_b128 v[128:131], v115 offset:96
	ds_read_b128 v[186:189], v115 offset:4672
	ds_read_b128 v[190:193], v115 offset:4704
	v_or_b32_e32 v0, s24, v133
	v_sub_u32_e32 v0, v102, v0
	v_cvt_f32_i32_e32 v0, v0
	v_mul_f32_e64 v0, -v105, v0
	v_cndmask_b32_e64 v0, v215, v0, s[0:1]
	s_setprio 1
	s_waitcnt lgkmcnt(7)
	v_mfma_f32_32x32x16_bf16 v[50:65], v[34:37], v[74:77], 0
	s_waitcnt lgkmcnt(5)
	v_mfma_f32_32x32x16_bf16 v[34:49], v[38:41], v[74:77], 0
	v_mfma_f32_32x32x16_bf16 v[50:65], v[116:119], v[70:73], v[50:65]
	s_waitcnt lgkmcnt(4)
	v_mfma_f32_32x32x16_bf16 v[34:49], v[120:123], v[70:73], v[34:49]
	s_waitcnt lgkmcnt(3)
	v_mfma_f32_32x32x16_bf16 v[50:65], v[124:127], v[66:69], v[50:65]
	s_waitcnt lgkmcnt(1)
	v_mfma_f32_32x32x16_bf16 v[34:49], v[186:189], v[66:69], v[34:49]
	v_mfma_f32_32x32x16_bf16 v[50:65], v[128:131], v[78:81], v[50:65]
	s_waitcnt lgkmcnt(0)
	v_mfma_f32_32x32x16_bf16 v[34:49], v[190:193], v[78:81], v[34:49]
	s_setprio 0
	s_nop 8
	v_add_f32_e32 v51, v105, v51
	s_nop 0
	v_fmamk_f32 v35, v105, 0x42040000, v35
	v_fma_f32 v50, 0, v105, v50
	v_fmamk_f32 v34, v105, 0x42000000, v34
	v_fma_f32 v52, 2.0, v105, v52
	v_fmamk_f32 v36, v105, 0x42080000, v36
	v_fmamk_f32 v53, v105, 0x40400000, v53
	v_fmamk_f32 v37, v105, 0x420c0000, v37
	v_max_f32_e32 v115, v51, v35
	v_fmamk_f32 v54, v105, 0x41000000, v54
	v_fmamk_f32 v38, v105, 0x42200000, v38
	v_fmamk_f32 v55, v105, 0x41100000, v55
	v_fmamk_f32 v39, v105, 0x42240000, v39
	v_max3_f32 v115, v50, v34, v115
	v_max_f32_e32 v116, v52, v36
	v_max_f32_e32 v117, v53, v37
	v_fmamk_f32 v56, v105, 0x41200000, v56
	v_fmamk_f32 v40, v105, 0x42280000, v40
	v_fmamk_f32 v57, v105, 0x41300000, v57
	v_fmamk_f32 v41, v105, 0x422c0000, v41
	v_max3_f32 v115, v115, v116, v117
	v_max_f32_e32 v116, v54, v38
	v_max_f32_e32 v117, v55, v39
	v_fmamk_f32 v58, v105, 0x41800000, v58
	v_fmamk_f32 v42, v105, 0x42400000, v42
	v_fmamk_f32 v59, v105, 0x41880000, v59
	v_fmamk_f32 v43, v105, 0x42440000, v43
	v_max3_f32 v115, v115, v116, v117
	v_max_f32_e32 v116, v56, v40
	v_max_f32_e32 v117, v57, v41
	v_fmamk_f32 v60, v105, 0x41900000, v60
	v_fmamk_f32 v44, v105, 0x42480000, v44
	v_fmamk_f32 v61, v105, 0x41980000, v61
	v_fmamk_f32 v45, v105, 0x424c0000, v45
	v_max3_f32 v115, v115, v116, v117
	v_max_f32_e32 v116, v58, v42
	v_max_f32_e32 v117, v59, v43
	v_fmamk_f32 v62, v105, 0x41c00000, v62
	v_fmamk_f32 v46, v105, 0x42600000, v46
	v_fmamk_f32 v63, v105, 0x41c80000, v63
	v_fmamk_f32 v47, v105, 0x42640000, v47
	v_max3_f32 v115, v115, v116, v117
	v_max_f32_e32 v116, v60, v44
	v_max_f32_e32 v117, v61, v45
	v_fmamk_f32 v64, v105, 0x41d00000, v64
; #define LAS __attribute__((address_space(3)))
; __device__ __forceinline__ float sum32(float v) { auto rr = __builtin_amdgcn_permlane32_swap(__float_as_uint(v), __float_as_uint(v), false, false); return __uint_as_float(rr[0]) + __uint_as_float(rr[1]); }
; #define EXP2(x) __builtin_amdgcn_exp2f(x)
; __device__ __forceinline__ void pv_accum(const f32x16& s0, const f32x16& s1, f32x16& o0, f32x16& o1, LAS const unsigned char* vtb, int r, int hh) {
;     __builtin_amdgcn_s_setprio(1);
; #pragma unroll
;     for (int kt = 0; kt < 2; ++kt)
; #pragma unroll
;         for (int sp = 0; sp < 2; ++sp) { u32x4 w;
;             if (kt == 0) { w.x = cvtpk(s0[8 * sp], s0[8 * sp + 1]); w.y = cvtpk(s0[8 * sp + 2], s0[8 * sp + 3]); w.z = cvtpk(s0[8 * sp + 4], s0[8 * sp + 5]); w.w = cvtpk(s0[8 * sp + 6], s0[8 * sp + 7]); }
;             else         { w.x = cvtpk(s1[8 * sp], s1[8 * sp + 1]); w.y = cvtpk(s1[8 * sp + 2], s1[8 * sp + 3]); w.z = cvtpk(s1[8 * sp + 4], s1[8 * sp + 5]); w.w = cvtpk(s1[8 * sp + 6], s1[8 * sp + 7]); }
;             const bf16x8 pb = __builtin_bit_cast(bf16x8, w); const int ko = 32 * kt + 16 * sp + 4 * hh;
;             { const s16x4 lo = *(LAS const s16x4*)(vtb + r * VTB + ko * 2), hi = *(LAS const s16x4*)(vtb + r * VTB + (ko + 8) * 2);
;               o0 = MFMA32(__builtin_shufflevector(lo, hi, 0, 1, 2, 3, 4, 5, 6, 7), pb, o0); }
;             { const s16x4 lo = *(LAS const s16x4*)(vtb + (32 + r) * VTB + ko * 2), hi = *(LAS const s16x4*)(vtb + (32 + r) * VTB + (ko + 8) * 2);
;               o1 = MFMA32(__builtin_shufflevector(lo, hi, 0, 1, 2, 3, 4, 5, 6, 7), pb, o1); } }
;     __builtin_amdgcn_s_setprio(0);
; }
; __device__ __forceinline__ void attn_block_full(const bf16x8 (&qf)[4], f32x16& o0, f32x16& o1, float& m, float& l, LAS const unsigned char* ksb, LAS const unsigned char* vtb, int r, int hh, float b0, float sl) {
;     ...
;     const float mnew = fmaxf(m, mloc), msafe = mnew == -INFINITY ? 0.f : mnew, corr = EXP2(m - msafe), c0 = b0 - msafe;
;     float psum = 0.f;
; #pragma unroll
;     for (int i = 0; i < 16; ++i) { s0[i] = EXP2(s0[i] + c0); s1[i] = EXP2(s1[i] + c0); psum += s0[i] + s1[i]; }
;     psum = sum32(psum);
;     l = l * corr + psum; m = mnew;
; #pragma unroll
;     for (int i = 0; i < 16; ++i) { o0[i] *= corr; o1[i] *= corr; }
;     __builtin_amdgcn_sched_barrier(0);
;     pv_accum(s0, s1, o0, o1, vtb, r, hh);
	v_fmamk_f32 v48, v105, 0x42680000, v48
	v_fmac_f32_e32 v65, 0x41d80000, v105
	v_fmac_f32_e32 v49, 0x426c0000, v105
	v_max3_f32 v115, v115, v116, v117
	v_max_f32_e32 v116, v62, v46
	v_max_f32_e32 v117, v63, v47
	v_max3_f32 v115, v115, v116, v117
	v_max_f32_e32 v116, v64, v48
	v_max_f32_e32 v117, v65, v49
	v_max3_f32 v115, v115, v116, v117
	v_add_f32_e32 v115, v0, v115
	v_mov_b32_e32 v116, v115
	s_nop 1
	v_permlane32_swap_b32_e32 v115, v116
	v_max3_f32 v185, v114, v115, v116
	v_cmp_neq_f32_e32 vcc, s34, v185
	s_nop 1
	v_cndmask_b32_e32 v115, 0, v185, vcc
	v_sub_f32_e32 v195, v0, v115
	v_add_f32_e32 v0, v50, v195
	v_exp_f32_e32 v196, v0
	v_add_f32_e32 v0, v34, v195
	v_exp_f32_e32 v197, v0
	v_add_f32_e32 v0, v51, v195
	v_exp_f32_e32 v128, v0
	v_add_f32_e32 v0, v35, v195
	v_exp_f32_e32 v0, v0
	v_add_f32_e32 v129, v196, v197
	v_sub_f32_e32 v194, v114, v115
	v_exp_f32_e32 v50, v194
	v_pk_add_f32 v[34:35], v[128:129], v[0:1]
	s_nop 0
	v_pk_add_f32 v[114:115], v[34:35], v[34:35] op_sel_hi:[0,1]
	v_add_f32_e32 v34, v52, v195
	v_exp_f32_e32 v129, v34
	v_add_f32_e32 v34, v36, v195
	v_exp_f32_e32 v198, v34
	v_add_f32_e32 v34, v53, v195
	v_exp_f32_e32 v140, v34
	v_add_f32_e32 v34, v37, v195
	v_exp_f32_e32 v114, v34
	v_add_f32_e32 v141, v129, v198
	v_pk_mul_f32 v[20:21], v[20:21], v[50:51] op_sel_hi:[1,0]
	v_pk_mul_f32 v[4:5], v[4:5], v[50:51] op_sel_hi:[1,0]
	v_pk_add_f32 v[34:35], v[140:141], v[114:115]
	s_nop 0
	v_pk_add_f32 v[118:119], v[34:35], v[34:35] op_sel_hi:[0,1]
	v_add_f32_e32 v34, v54, v195
	v_exp_f32_e32 v115, v34
	v_add_f32_e32 v34, v38, v195
	v_exp_f32_e32 v141, v34
	v_add_f32_e32 v34, v55, v195
	v_exp_f32_e32 v146, v34
	v_add_f32_e32 v34, v39, v195
	v_exp_f32_e32 v118, v34
	v_add_f32_e32 v147, v115, v141
	v_pk_mul_f32 v[22:23], v[22:23], v[50:51] op_sel_hi:[1,0]
	v_pk_mul_f32 v[6:7], v[6:7], v[50:51] op_sel_hi:[1,0]
	v_pk_add_f32 v[34:35], v[146:147], v[118:119]
	s_nop 0
	v_pk_add_f32 v[122:123], v[34:35], v[34:35] op_sel_hi:[0,1]
	v_add_f32_e32 v34, v56, v195
	v_exp_f32_e32 v119, v34
	v_add_f32_e32 v34, v40, v195
	v_exp_f32_e32 v147, v34
	v_add_f32_e32 v34, v57, v195
	v_exp_f32_e32 v186, v34
	v_add_f32_e32 v34, v41, v195
	v_exp_f32_e32 v122, v34
	v_add_f32_e32 v187, v119, v147
	v_pk_mul_f32 v[24:25], v[24:25], v[50:51] op_sel_hi:[1,0]
	v_pk_mul_f32 v[8:9], v[8:9], v[50:51] op_sel_hi:[1,0]
	v_pk_add_f32 v[34:35], v[186:187], v[122:123]
	s_nop 0
	v_pk_add_f32 v[116:117], v[34:35], v[34:35] op_sel_hi:[0,1]
	v_add_f32_e32 v34, v58, v195
	v_exp_f32_e32 v123, v34
	v_add_f32_e32 v34, v42, v195
	v_exp_f32_e32 v187, v34
	v_add_f32_e32 v34, v59, v195
	v_exp_f32_e32 v130, v34
	v_add_f32_e32 v34, v43, v195
	v_exp_f32_e32 v116, v34
	v_add_f32_e32 v131, v123, v187
	v_pk_mul_f32 v[26:27], v[26:27], v[50:51] op_sel_hi:[1,0]
	v_pk_mul_f32 v[10:11], v[10:11], v[50:51] op_sel_hi:[1,0]
	v_pk_add_f32 v[34:35], v[130:131], v[116:117]
	s_nop 0
	v_pk_add_f32 v[120:121], v[34:35], v[34:35] op_sel_hi:[0,1]
	v_add_f32_e32 v34, v60, v195
	v_exp_f32_e32 v131, v34
	v_add_f32_e32 v34, v44, v195
	v_exp_f32_e32 v199, v34
	v_add_f32_e32 v34, v61, v195
	v_exp_f32_e32 v188, v34
	v_add_f32_e32 v34, v45, v195
	v_exp_f32_e32 v120, v34
	v_add_f32_e32 v189, v131, v199
	v_pk_mul_f32 v[28:29], v[28:29], v[50:51] op_sel_hi:[1,0]
	v_pk_mul_f32 v[12:13], v[12:13], v[50:51] op_sel_hi:[1,0]
	v_pk_add_f32 v[34:35], v[188:189], v[120:121]
	s_nop 0
	v_pk_add_f32 v[124:125], v[34:35], v[34:35] op_sel_hi:[0,1]
	v_add_f32_e32 v34, v62, v195
	v_exp_f32_e32 v121, v34
	v_add_f32_e32 v34, v46, v195
	v_exp_f32_e32 v189, v34
	v_add_f32_e32 v34, v63, v195
	v_exp_f32_e32 v190, v34
	v_add_f32_e32 v34, v47, v195
	v_exp_f32_e32 v124, v34
	v_add_f32_e32 v191, v121, v189
	v_pk_mul_f32 v[30:31], v[30:31], v[50:51] op_sel_hi:[1,0]
	v_pk_mul_f32 v[14:15], v[14:15], v[50:51] op_sel_hi:[1,0]
	v_pk_add_f32 v[34:35], v[190:191], v[124:125]
	s_nop 0
	v_pk_add_f32 v[126:127], v[34:35], v[34:35] op_sel_hi:[0,1]
	v_add_f32_e32 v34, v64, v195
	v_exp_f32_e32 v125, v34
	v_add_f32_e32 v34, v48, v195
	v_exp_f32_e32 v191, v34
	v_add_f32_e32 v34, v65, v195
	v_exp_f32_e32 v192, v34
	v_add_f32_e32 v34, v49, v195
	v_exp_f32_e32 v126, v34
	v_add_f32_e32 v193, v125, v191
	v_pk_mul_f32 v[32:33], v[32:33], v[50:51] op_sel_hi:[1,0]
	v_pk_mul_f32 v[16:17], v[16:17], v[50:51] op_sel_hi:[1,0]
	v_pk_add_f32 v[34:35], v[192:193], v[126:127]
	s_nop 0
	v_pk_add_f32 v[34:35], v[34:35], v[34:35] op_sel:[0,1] op_sel_hi:[1,0]
	s_nop 0
	v_mov_b32_e32 v35, v34
	s_nop 1
	v_permlane32_swap_b32_e32 v34, v35
	v_add_f32_e32 v117, v34, v35
	v_fmac_f32_e32 v117, v184, v50
	v_pk_mul_f32 v[18:19], v[18:19], v[50:51] op_sel_hi:[1,0]
	v_pk_mul_f32 v[2:3], v[2:3], v[50:51] op_sel_hi:[1,0]
	s_setprio 1
	v_add3_u32 v46, s44, v151, v132
	v_add_u32_e32 v47, 0x4800, v46
	ds_read2_b64 v[38:41], v47 offset1:2
	ds_read2_b64 v[42:45], v47 offset0:4 offset1:6
	v_cvt_pk_bf16_f32 v34, v196, v128
	v_cvt_pk_bf16_f32 v35, v129, v140
	v_cvt_pk_bf16_f32 v36, v115, v146
	v_cvt_pk_bf16_f32 v37, v119, v186
	v_add_u32_e32 v46, 0x5800, v46
	s_waitcnt lgkmcnt(1)
	v_mfma_f32_32x32x16_bf16 v[18:33], v[38:41], v[34:37], v[18:33]
	ds_read2_b64 v[38:41], v46 offset0:32 offset1:34
	s_waitcnt lgkmcnt(0)
	v_mfma_f32_32x32x16_bf16 v[2:17], v[38:41], v[34:37], v[2:17]
	ds_read2_b64 v[38:41], v46 offset0:36 offset1:38
	v_cvt_pk_bf16_f32 v34, v123, v130
	v_cvt_pk_bf16_f32 v35, v131, v188
	v_cvt_pk_bf16_f32 v36, v121, v190
	v_cvt_pk_bf16_f32 v37, v125, v192
	s_waitcnt lgkmcnt(0)
	s_nop 0
	v_mfma_f32_32x32x16_bf16 v[2:17], v[38:41], v[34:37], v[2:17]
	ds_read2_b64 v[38:41], v47 offset0:8 offset1:10
	v_mfma_f32_32x32x16_bf16 v[18:33], v[42:45], v[34:37], v[18:33]
	v_cvt_pk_bf16_f32 v34, v197, v0
	v_cvt_pk_bf16_f32 v35, v198, v114
	v_cvt_pk_bf16_f32 v36, v141, v118
	v_cvt_pk_bf16_f32 v37, v147, v122
	s_waitcnt lgkmcnt(0)
	s_nop 0
	v_mfma_f32_32x32x16_bf16 v[18:33], v[38:41], v[34:37], v[18:33]
	ds_read2_b64 v[38:41], v46 offset0:40 offset1:42
	s_waitcnt lgkmcnt(0)
	v_mfma_f32_32x32x16_bf16 v[2:17], v[38:41], v[34:37], v[2:17]
	ds_read2_b64 v[38:41], v47 offset0:12 offset1:14
	v_cvt_pk_bf16_f32 v34, v187, v116
	v_cvt_pk_bf16_f32 v35, v199, v120
	v_cvt_pk_bf16_f32 v36, v189, v124
	v_cvt_pk_bf16_f32 v37, v191, v126
	s_waitcnt lgkmcnt(0)
	s_nop 0
	v_mfma_f32_32x32x16_bf16 v[18:33], v[38:41], v[34:37], v[18:33]
	ds_read2_b64 v[38:41], v46 offset0:44 offset1:46
	s_waitcnt lgkmcnt(0)
	v_mfma_f32_32x32x16_bf16 v[2:17], v[38:41], v[34:37], v[2:17]
.LBB0_1300:
	s_setprio 0
	s_nop 7
	s_nop 1
	v_mov_b32_e32 v114, v185
	v_mov_b32_e32 v184, v117

; #define LAS __attribute__((address_space(3)))
; __device__ __forceinline__ float sum32(float v) { auto rr = __builtin_amdgcn_permlane32_swap(__float_as_uint(v), __float_as_uint(v), false, false); return __uint_as_float(rr[0]) + __uint_as_float(rr[1]); }
; __device__ __forceinline__ float max32(float v) { auto rr = __builtin_amdgcn_permlane32_swap(__float_as_uint(v), __float_as_uint(v), false, false); return fmaxf(__uint_as_float(rr[0]), __uint_as_float(rr[1])); }
; #define MFMA32(a, b, c) __builtin_amdgcn_mfma_f32_32x32x16_bf16((a), (b), (c), 0, 0, 0)
; #define EXP2(x) __builtin_amdgcn_exp2f(x)
; __device__ __forceinline__ void attn_block_full(const bf16x8 (&qf)[4], f32x16& o0, f32x16& o1, float& m, float& l, LAS const unsigned char* ksb, LAS const unsigned char* vtb, int r, int hh, float b0, float sl) {
;     f32x16 s0, s1;
; #pragma unroll
;     for (int i = 0; i < 16; ++i) { s0[i] = 0.f; s1[i] = 0.f; }
;     bf16x8 ka[4], kb2[4];
; #pragma unroll
;     for (int s = 0; s < 4; ++s) { ka[s] = *(LAS const bf16x8*)(ksb + r * KSB + (16 * s + 8 * hh) * 2); kb2[s] = *(LAS const bf16x8*)(ksb + (32 + r) * KSB + (16 * s + 8 * hh) * 2); }
;     __builtin_amdgcn_s_setprio(1);
; #pragma unroll
;     for (int s = 0; s < 4; ++s) { s0 = MFMA32(ka[s], qf[s], s0); s1 = MFMA32(kb2[s], qf[s], s1); }
;     __builtin_amdgcn_s_setprio(0);
;     __builtin_amdgcn_sched_barrier(0);
; #pragma unroll
;     for (int i = 0; i < 16; ++i) { const float c = (float)((i & 3) + 8 * (i >> 2)); s0[i] = fmaf(sl, c, s0[i]); s1[i] = fmaf(sl, c + 32.f, s1[i]); }
;     float mloc = fmaxf(s0[0], s1[0]);
; #pragma unroll
;     for (int i = 1; i < 16; ++i) mloc = fmaxf(mloc, fmaxf(s0[i], s1[i]));
;     mloc = max32(mloc + b0);
;     const float mnew = fmaxf(m, mloc), msafe = mnew == -INFINITY ? 0.f : mnew, corr = EXP2(m - msafe), c0 = b0 - msafe;
;     float psum = 0.f;
; #pragma unroll
;     for (int i = 0; i < 16; ++i) { s0[i] = EXP2(s0[i] + c0); s1[i] = EXP2(s1[i] + c0); psum += s0[i] + s1[i]; }
;     psum = sum32(psum);
;     l = l * corr + psum; m = mnew;
.LBB0_1306:
	s_cmp_ge_u32 s8, s19
	s_cselect_b64 s[0:1], -1, 0
	s_cmp_lt_i32 s8, s6
	v_cvt_f32_i32_e32 v130, v124
	s_cselect_b64 s[40:41], -1, 0
	s_or_b64 s[40:41], s[0:1], s[40:41]
	s_mov_b64 s[0:1], -1
	s_and_b64 vcc, exec, s[40:41]
	v_add3_u32 v131, s9, v150, v104
	v_add3_u32 v127, s24, v151, v132
	s_cbranch_vccnz .LBB0_1308
	ds_read_b128 v[34:37], v131
	ds_read_b128 v[112:115], v131 offset:32
	ds_read_b128 v[38:41], v131 offset:4608
	ds_read_b128 v[116:119], v131 offset:4640
	ds_read_b128 v[120:123], v131 offset:64
	ds_read_b128 v[154:157], v131 offset:96
	ds_read_b128 v[158:161], v131 offset:4672
	ds_read_b128 v[162:165], v131 offset:4704
	s_setprio 1
	s_waitcnt lgkmcnt(7)
	v_mfma_f32_32x32x16_bf16 v[50:65], v[34:37], v[74:77], 0
	s_waitcnt lgkmcnt(5)
	v_mfma_f32_32x32x16_bf16 v[34:49], v[38:41], v[74:77], 0
	v_mfma_f32_32x32x16_bf16 v[50:65], v[112:115], v[70:73], v[50:65]
	s_waitcnt lgkmcnt(4)
	v_mfma_f32_32x32x16_bf16 v[34:49], v[116:119], v[70:73], v[34:49]
	s_waitcnt lgkmcnt(3)
	v_mfma_f32_32x32x16_bf16 v[50:65], v[120:123], v[66:69], v[50:65]
	s_waitcnt lgkmcnt(1)
	v_mfma_f32_32x32x16_bf16 v[34:49], v[158:161], v[66:69], v[34:49]
	v_mfma_f32_32x32x16_bf16 v[50:65], v[154:157], v[78:81], v[50:65]
	s_waitcnt lgkmcnt(0)
	v_mfma_f32_32x32x16_bf16 v[34:49], v[162:165], v[78:81], v[34:49]
	s_setprio 0
	s_nop 8
	v_fma_f32 v0, 0, v105, v50
	v_add_f32_e32 v50, v105, v51
	v_fmamk_f32 v35, v105, 0x42040000, v35
	v_fmamk_f32 v34, v105, 0x42000000, v34
	v_fma_f32 v51, 2.0, v105, v52
	v_fmamk_f32 v36, v105, 0x42080000, v36
	v_fmamk_f32 v52, v105, 0x40400000, v53
	v_fmamk_f32 v37, v105, 0x420c0000, v37
	v_fmamk_f32 v53, v105, 0x41000000, v54
	v_fmamk_f32 v54, v105, 0x41100000, v55
	v_fmamk_f32 v55, v105, 0x41200000, v56
	v_fmamk_f32 v56, v105, 0x41300000, v57
	v_fmamk_f32 v57, v105, 0x41800000, v58
	v_fmamk_f32 v58, v105, 0x41880000, v59
	v_fmamk_f32 v59, v105, 0x41900000, v60
	v_fmamk_f32 v60, v105, 0x41980000, v61
	v_fmamk_f32 v61, v105, 0x41c00000, v62
	v_fmamk_f32 v62, v105, 0x41c80000, v63
	v_fmamk_f32 v63, v105, 0x41d00000, v64
	v_max_f32_e32 v64, v50, v35
	v_fmamk_f32 v38, v105, 0x42200000, v38
	v_fmamk_f32 v39, v105, 0x42240000, v39
	v_max3_f32 v64, v0, v34, v64
	v_max_f32_e32 v106, v51, v36
	v_max_f32_e32 v107, v52, v37
	v_fmamk_f32 v40, v105, 0x42280000, v40
	v_fmamk_f32 v41, v105, 0x422c0000, v41
	v_max3_f32 v64, v64, v106, v107
	v_max_f32_e32 v106, v53, v38
	v_max_f32_e32 v107, v54, v39
	v_fmamk_f32 v42, v105, 0x42400000, v42
	v_fmamk_f32 v43, v105, 0x42440000, v43
	v_max3_f32 v64, v64, v106, v107
	v_max_f32_e32 v106, v55, v40
	v_max_f32_e32 v107, v56, v41
	v_fmamk_f32 v44, v105, 0x42480000, v44
	v_fmamk_f32 v45, v105, 0x424c0000, v45
	v_max3_f32 v64, v64, v106, v107
	v_max_f32_e32 v106, v57, v42
	v_max_f32_e32 v107, v58, v43
	v_fmamk_f32 v46, v105, 0x42600000, v46
	v_fmamk_f32 v47, v105, 0x42640000, v47
	v_max3_f32 v64, v64, v106, v107
	v_max_f32_e32 v106, v59, v44
	v_max_f32_e32 v107, v60, v45
	v_fmamk_f32 v48, v105, 0x42680000, v48
	v_fmac_f32_e32 v65, 0x41d80000, v105
	v_fmac_f32_e32 v49, 0x426c0000, v105
	v_max3_f32 v64, v64, v106, v107
	v_max_f32_e32 v106, v61, v46
	v_max_f32_e32 v107, v62, v47
	v_max3_f32 v64, v64, v106, v107
	v_max_f32_e32 v106, v63, v48
	v_max_f32_e32 v107, v65, v49
	v_max3_f32 v64, v64, v106, v107
	v_fma_f32 v64, -v105, v130, v64
	v_mov_b32_e32 v106, v64
	s_nop 1
	v_permlane32_swap_b32_e32 v64, v106
	v_max3_f32 v129, v128, v64, v106
	v_cmp_neq_f32_e32 vcc, s34, v129
	s_nop 1
	v_cndmask_b32_e32 v64, 0, v129, vcc
	v_fma_f32 v134, -v105, v130, -v64
	v_add_f32_e32 v0, v0, v134
	v_exp_f32_e32 v152, v0
	v_add_f32_e32 v0, v34, v134
	v_exp_f32_e32 v174, v0
	v_add_f32_e32 v0, v50, v134
	v_exp_f32_e32 v140, v0
	v_add_f32_e32 v0, v35, v134
	v_exp_f32_e32 v0, v0
	v_add_f32_e32 v141, v152, v174
	v_pk_add_f32 v[34:35], v[140:141], v[0:1]
	s_nop 0
	v_pk_add_f32 v[112:113], v[34:35], v[34:35] op_sel_hi:[0,1]
	v_add_f32_e32 v34, v51, v134
	v_exp_f32_e32 v141, v34
	v_add_f32_e32 v34, v36, v134
	v_exp_f32_e32 v175, v34
	v_add_f32_e32 v34, v52, v134
	v_exp_f32_e32 v146, v34
	v_add_f32_e32 v34, v37, v134
	v_exp_f32_e32 v112, v34
	v_add_f32_e32 v147, v141, v175
	v_sub_f32_e32 v36, v128, v64
	v_exp_f32_e32 v50, v36
	v_pk_add_f32 v[34:35], v[146:147], v[112:113]
	v_pk_mul_f32 v[20:21], v[20:21], v[50:51] op_sel_hi:[1,0]
	v_pk_add_f32 v[116:117], v[34:35], v[34:35] op_sel_hi:[0,1]
	v_add_f32_e32 v34, v53, v134
	v_exp_f32_e32 v113, v34
	v_add_f32_e32 v34, v38, v134
	v_exp_f32_e32 v147, v34
	v_add_f32_e32 v34, v54, v134
	v_exp_f32_e32 v156, v34
	v_add_f32_e32 v34, v39, v134
	v_exp_f32_e32 v116, v34
	v_add_f32_e32 v157, v113, v147
	v_pk_mul_f32 v[22:23], v[22:23], v[50:51] op_sel_hi:[1,0]
; #define LAS __attribute__((address_space(3)))
; __device__ __forceinline__ float sum32(float v) { auto rr = __builtin_amdgcn_permlane32_swap(__float_as_uint(v), __float_as_uint(v), false, false); return __uint_as_float(rr[0]) + __uint_as_float(rr[1]); }
; #define EXP2(x) __builtin_amdgcn_exp2f(x)
; __device__ __forceinline__ void pv_accum(const f32x16& s0, const f32x16& s1, f32x16& o0, f32x16& o1, LAS const unsigned char* vtb, int r, int hh) {
;     __builtin_amdgcn_s_setprio(1);
; #pragma unroll
;     for (int kt = 0; kt < 2; ++kt)
; #pragma unroll
;         for (int sp = 0; sp < 2; ++sp) { u32x4 w;
;             if (kt == 0) { w.x = cvtpk(s0[8 * sp], s0[8 * sp + 1]); w.y = cvtpk(s0[8 * sp + 2], s0[8 * sp + 3]); w.z = cvtpk(s0[8 * sp + 4], s0[8 * sp + 5]); w.w = cvtpk(s0[8 * sp + 6], s0[8 * sp + 7]); }
;             else         { w.x = cvtpk(s1[8 * sp], s1[8 * sp + 1]); w.y = cvtpk(s1[8 * sp + 2], s1[8 * sp + 3]); w.z = cvtpk(s1[8 * sp + 4], s1[8 * sp + 5]); w.w = cvtpk(s1[8 * sp + 6], s1[8 * sp + 7]); }
;             const bf16x8 pb = __builtin_bit_cast(bf16x8, w); const int ko = 32 * kt + 16 * sp + 4 * hh;
;             { const s16x4 lo = *(LAS const s16x4*)(vtb + r * VTB + ko * 2), hi = *(LAS const s16x4*)(vtb + r * VTB + (ko + 8) * 2);
;               o0 = MFMA32(__builtin_shufflevector(lo, hi, 0, 1, 2, 3, 4, 5, 6, 7), pb, o0); }
;             { const s16x4 lo = *(LAS const s16x4*)(vtb + (32 + r) * VTB + ko * 2), hi = *(LAS const s16x4*)(vtb + (32 + r) * VTB + (ko + 8) * 2);
;               o1 = MFMA32(__builtin_shufflevector(lo, hi, 0, 1, 2, 3, 4, 5, 6, 7), pb, o1); } }
;     __builtin_amdgcn_s_setprio(0);
; }
; __device__ __forceinline__ void attn_block_full(const bf16x8 (&qf)[4], f32x16& o0, f32x16& o1, float& m, float& l, LAS const unsigned char* ksb, LAS const unsigned char* vtb, int r, int hh, float b0, float sl) {
;     ...
;     const float mnew = fmaxf(m, mloc), msafe = mnew == -INFINITY ? 0.f : mnew, corr = EXP2(m - msafe), c0 = b0 - msafe;
;     float psum = 0.f;
; #pragma unroll
;     for (int i = 0; i < 16; ++i) { s0[i] = EXP2(s0[i] + c0); s1[i] = EXP2(s1[i] + c0); psum += s0[i] + s1[i]; }
;     psum = sum32(psum);
;     l = l * corr + psum; m = mnew;
; #pragma unroll
;     for (int i = 0; i < 16; ++i) { o0[i] *= corr; o1[i] *= corr; }
;     __builtin_amdgcn_sched_barrier(0);
;     pv_accum(s0, s1, o0, o1, vtb, r, hh);
	v_pk_mul_f32 v[4:5], v[4:5], v[50:51] op_sel_hi:[1,0]
	v_pk_add_f32 v[34:35], v[156:157], v[116:117]
	s_nop 0
	v_pk_add_f32 v[120:121], v[34:35], v[34:35] op_sel_hi:[0,1]
	v_add_f32_e32 v34, v55, v134
	v_exp_f32_e32 v117, v34
	v_add_f32_e32 v34, v40, v134
	v_exp_f32_e32 v176, v34
	v_add_f32_e32 v34, v56, v134
	v_exp_f32_e32 v158, v34
	v_add_f32_e32 v34, v41, v134
	v_exp_f32_e32 v120, v34
	v_add_f32_e32 v159, v117, v176
	v_pk_mul_f32 v[24:25], v[24:25], v[50:51] op_sel_hi:[1,0]
	v_pk_mul_f32 v[6:7], v[6:7], v[50:51] op_sel_hi:[1,0]
	v_pk_add_f32 v[34:35], v[158:159], v[120:121]
	s_nop 0
	v_pk_add_f32 v[106:107], v[34:35], v[34:35] op_sel_hi:[0,1]
	v_add_f32_e32 v34, v57, v134
	v_exp_f32_e32 v121, v34
	v_add_f32_e32 v34, v42, v134
	v_exp_f32_e32 v177, v34
	v_add_f32_e32 v34, v58, v134
	v_exp_f32_e32 v166, v34
	v_add_f32_e32 v34, v43, v134
	v_exp_f32_e32 v106, v34
	v_add_f32_e32 v167, v121, v177
	v_pk_mul_f32 v[26:27], v[26:27], v[50:51] op_sel_hi:[1,0]
	v_pk_mul_f32 v[8:9], v[8:9], v[50:51] op_sel_hi:[1,0]
	v_pk_add_f32 v[34:35], v[166:167], v[106:107]
	s_nop 0
	v_pk_add_f32 v[114:115], v[34:35], v[34:35] op_sel_hi:[0,1]
	v_add_f32_e32 v34, v59, v134
	v_exp_f32_e32 v167, v34
	v_add_f32_e32 v34, v44, v134
	v_exp_f32_e32 v178, v34
	v_add_f32_e32 v34, v60, v134
	v_exp_f32_e32 v168, v34
	v_add_f32_e32 v34, v45, v134
	v_exp_f32_e32 v114, v34
	v_add_f32_e32 v169, v167, v178
	v_pk_mul_f32 v[28:29], v[28:29], v[50:51] op_sel_hi:[1,0]
	v_pk_mul_f32 v[10:11], v[10:11], v[50:51] op_sel_hi:[1,0]
	v_pk_add_f32 v[34:35], v[168:169], v[114:115]
	s_nop 0
	v_pk_add_f32 v[118:119], v[34:35], v[34:35] op_sel_hi:[0,1]
	v_add_f32_e32 v34, v61, v134
	v_exp_f32_e32 v115, v34
	v_add_f32_e32 v34, v46, v134
	v_exp_f32_e32 v169, v34
	v_add_f32_e32 v34, v62, v134
	v_exp_f32_e32 v170, v34
	v_add_f32_e32 v34, v47, v134
	v_exp_f32_e32 v118, v34
	v_add_f32_e32 v171, v115, v169
	v_pk_mul_f32 v[30:31], v[30:31], v[50:51] op_sel_hi:[1,0]
	v_pk_mul_f32 v[12:13], v[12:13], v[50:51] op_sel_hi:[1,0]
	v_pk_add_f32 v[34:35], v[170:171], v[118:119]
	s_nop 0
	v_pk_add_f32 v[122:123], v[34:35], v[34:35] op_sel_hi:[0,1]
	v_add_f32_e32 v34, v63, v134
	v_exp_f32_e32 v119, v34
	v_add_f32_e32 v34, v48, v134
	v_exp_f32_e32 v171, v34
	v_add_f32_e32 v34, v65, v134
	v_exp_f32_e32 v172, v34
	v_add_f32_e32 v34, v49, v134
	v_exp_f32_e32 v122, v34
	v_add_f32_e32 v173, v119, v171
	v_pk_mul_f32 v[32:33], v[32:33], v[50:51] op_sel_hi:[1,0]
	v_pk_mul_f32 v[16:17], v[16:17], v[50:51] op_sel_hi:[1,0]
	v_pk_add_f32 v[34:35], v[172:173], v[122:123]
	v_pk_mul_f32 v[14:15], v[14:15], v[50:51] op_sel_hi:[1,0]
	v_pk_add_f32 v[34:35], v[34:35], v[34:35] op_sel:[0,1] op_sel_hi:[1,0]
	s_nop 0
	v_mov_b32_e32 v35, v34
	s_nop 1
	v_permlane32_swap_b32_e32 v34, v35
	v_add_f32_e32 v107, v34, v35
	v_fmac_f32_e32 v107, v126, v50
	v_pk_mul_f32 v[18:19], v[18:19], v[50:51] op_sel_hi:[1,0]
	v_pk_mul_f32 v[2:3], v[2:3], v[50:51] op_sel_hi:[1,0]
	s_setprio 1
	v_cvt_pk_bf16_f32 v157, v117, v158
	v_add_u32_e32 v117, 0x4800, v127
	ds_read2_b64 v[158:161], v117 offset1:2
	ds_read2_b64 v[162:165], v117 offset0:4 offset1:6
	v_cvt_pk_bf16_f32 v154, v152, v140
	v_cvt_pk_bf16_f32 v155, v141, v146
	v_cvt_pk_bf16_f32 v156, v113, v156
	v_add_u32_e32 v123, 0x5800, v127
	v_cvt_pk_bf16_f32 v113, v178, v114
	s_waitcnt lgkmcnt(1)
	v_mfma_f32_32x32x16_bf16 v[18:33], v[158:161], v[154:157], v[18:33]
	ds_read2_b64 v[158:161], v123 offset0:32 offset1:34
	v_cvt_pk_bf16_f32 v114, v169, v118
	s_mov_b64 s[0:1], 0
	s_waitcnt lgkmcnt(0)
	v_mfma_f32_32x32x16_bf16 v[2:17], v[158:161], v[154:157], v[2:17]
	ds_read2_b64 v[158:161], v123 offset0:36 offset1:38
	v_cvt_pk_bf16_f32 v154, v121, v166
	v_cvt_pk_bf16_f32 v155, v167, v168
	v_cvt_pk_bf16_f32 v156, v115, v170
	v_cvt_pk_bf16_f32 v157, v119, v172
	v_cvt_pk_bf16_f32 v115, v171, v122
	s_waitcnt lgkmcnt(0)
	v_mfma_f32_32x32x16_bf16 v[2:17], v[158:161], v[154:157], v[2:17]
	ds_read2_b64 v[158:161], v117 offset0:8 offset1:10
	v_mfma_f32_32x32x16_bf16 v[18:33], v[162:165], v[154:157], v[18:33]
	v_cvt_pk_bf16_f32 v154, v174, v0
	v_cvt_pk_bf16_f32 v155, v175, v112
	v_cvt_pk_bf16_f32 v156, v147, v116
	v_cvt_pk_bf16_f32 v157, v176, v120
	ds_read2_b64 v[116:119], v117 offset0:12 offset1:14
	v_cvt_pk_bf16_f32 v112, v177, v106
	s_waitcnt lgkmcnt(1)
	v_mfma_f32_32x32x16_bf16 v[18:33], v[158:161], v[154:157], v[18:33]
	ds_read2_b64 v[158:161], v123 offset0:40 offset1:42
	s_waitcnt lgkmcnt(1)
	v_mfma_f32_32x32x16_bf16 v[18:33], v[116:119], v[112:115], v[18:33]
	ds_read2_b64 v[116:119], v123 offset0:44 offset1:46
	s_waitcnt lgkmcnt(1)
	v_mfma_f32_32x32x16_bf16 v[2:17], v[158:161], v[154:157], v[2:17]
	s_waitcnt lgkmcnt(0)
	v_mfma_f32_32x32x16_bf16 v[2:17], v[116:119], v[112:115], v[2:17]

; __device__ __forceinline__ void nsa_item(const NsaArgs& A, int b, int tl, LAS unsigned char* lds, int tid) {
;     ...
;         KV_PIPELINE_PRE(nlo, (cur + 1 <= tl ? cur + 1 : -1), kp + (size_t)id * 4096, vp + (size_t)id * 4096,
;             { if (id < tl && id >= tl - 7) attn_block_full(qf, o0, o1, m, l, ksb, vtb, r, hh, -slope * (float)(tq - 64 * id - 4 * hh), slope);
;               else { const SfWin sf{tq, 64 * id, slope}; attn_block<0>(qf, o0, o1, m, l, ksb, vtb, r, hh, sf, 0.f, 0.f, nullptr, 0, dummy); } });
;         const float sc = gl[2] / l;
; #pragma unroll
;         for (int i = 0; i < 16; ++i) { of0[i] = park[i * 64] + sc * o0[i]; of1[i] = park[(16 + i) * 64] + sc * o1[i]; }
.LBB0_1312:
	s_setprio 0
	s_xor_b32 s7, s7, 1
	v_subrev_u32_e32 v124, 64, v124
	s_andn2_b64 vcc, exec, s[4:5]
	v_add_u32_e32 v125, 64, v125
	s_cbranch_vccz .Lwin_exit
	s_nop 2
	s_mov_b32 s0, s8
	v_mov_b32_e32 v126, v107
	v_mov_b32_e32 v128, v129
	s_branch .LBB0_1304
.Lwin_exit:
	s_nop 7
	s_nop 3
	v_mov_b64_e32 v[34:35], v[18:19]
	v_mov_b64_e32 v[36:37], v[20:21]
	v_mov_b64_e32 v[38:39], v[22:23]
	v_mov_b64_e32 v[40:41], v[24:25]
	v_mov_b64_e32 v[42:43], v[26:27]
	v_mov_b64_e32 v[44:45], v[28:29]
	v_mov_b64_e32 v[46:47], v[30:31]
	v_mov_b64_e32 v[48:49], v[32:33]
	v_mov_b64_e32 v[50:51], v[2:3]
	v_mov_b64_e32 v[52:53], v[4:5]
	v_mov_b64_e32 v[54:55], v[6:7]
	v_mov_b64_e32 v[56:57], v[8:9]
	v_mov_b64_e32 v[58:59], v[10:11]
	v_mov_b64_e32 v[60:61], v[12:13]
	v_mov_b64_e32 v[62:63], v[14:15]
	v_mov_b64_e32 v[64:65], v[16:17]
	s_branch .LBB0_1153
